# adds: static s_setprio of waves 4-7 in the diff-attention loop removed (timing-only)
# speedup vs baseline: 1.0085x; 1.0085x over previous
; DI int tid_() { int t = threadIdx.x; asm volatile("" : "+v"(t)); return t; }
; DI void diff_unit(KP p, int l, int b, int h, int qb, int isctx, float lamv, float lam_init, char* ldsc) {
;   const int tid = tid_(), lane = tid & 63, w = __builtin_amdgcn_readfirstlane(tid >> 6), r = lane & 31, hh = lane >> 5;
;   const int pr = (r & ~12) | ((r & 4) << 1) | ((r & 8) >> 1);
;   const int comp = w & 1, grp = w >> 1;
;   const int qrow = (isctx ? TL + b * CTXL : b * SEQ) + qb * 128 + grp * 32 + r;
;   const int nt = isctx ? 4 : 132;
;   lds_u8* L = (lds_u8*)ldsc;
;   constexpr int STG = 32768;
;   int ko[4], vo[4];
; #pragma unroll
;   for (int ks = 0; ks < 4; ++ks) ko[ks] = pr * 128 + (((2 * ks + hh) ^ ((pr >> 1) & 7)) << 4);
; #pragma unroll
;   for (int q = 0; q < 4; ++q) vo[q] = r * 128 + (((2 * q + hh) ^ ((r >> 1) & 7)) << 4);
;   bf16x8 qf[4];
; #pragma unroll
;   for (int ks = 0; ks < 4; ++ks) qf[ks] = *(const bf16x8*)(p->P + (size_t)qrow * INC + 512 + h * 128 + comp * 64 + 16 * ks + 8 * hh);
;   f32x16 o[4];
; #pragma unroll
;   for (int d = 0; d < 4; ++d)
; #pragma unroll
;     for (int i = 0; i < 16; ++i) o[d][i] = 0.f;
;   float m, lsum;
;   const bf16_t* vt = p->Vtd + (size_t)((b * 4 + h) * 128) * NKEY;
;   const bf16_t* Pk = p->P + 1024 + h * 128;
;   const int row8 = 8 * w + (lane >> 3), swz = ((lane & 7) ^ ((row8 >> 1) & 7)) << 4;
;   const unsigned kq = (unsigned)(row8 * (INC * 2) + swz), vq = (unsigned)(row8 * (NKEY * 2) + swz);
;     ...
;   asm volatile("s_waitcnt vmcnt(0)" ::: "memory");
;   __syncthreads();
;   DISSUE(0, 0);
;   DISSUE(1, 1);
;   asm volatile("s_waitcnt vmcnt(4)" ::: "memory");
;   __builtin_amdgcn_s_barrier();
;   bf16x8 P[4];
;   {
;     f32x16 st[2];
;     qk_tile(qf, L + comp * 8192, ko, st);
;     m = tile_max(st);
;     lsum = exp_pack(st, m, P);
;   }
;   int stg = 0;
;   bool need = false; float alpha = 1.f;
;   if (w >= 4) __builtin_amdgcn_s_setprio(1);
.LBB0_468:
	s_lshl_b32 s1, s12, 5
	s_and_b32 s0, s12, 0xffffff00
	s_and_b32 s1, s1, 0xe0
	s_or_b32 s0, s1, s0
	s_bfe_u32 s1, s12, 0x50003
	v_mov_b32_e32 v38, v158
	s_or_b32 s2, s0, s1
	s_and_b64 s[0:1], s[6:7], exec
	v_lshlrev_b32_e32 v2, 1, v38
	v_lshrrev_b32_e32 v34, 1, v38
	v_and_b32_e32 v0, 19, v38
	v_and_b32_e32 v2, 8, v2
	v_and_b32_e32 v3, 4, v34
	s_load_dwordx2 s[10:11], s[80:81], 0xf8
	s_cselect_b32 s2, s2, s12
	v_or3_b32 v0, v2, v0, v3
	s_ashr_i32 s13, s2, 8
	v_readfirstlane_b32 s1, v38
	v_bfe_u32 v144, v38, 5, 1
	s_lshl_b32 s4, s2, 7
	v_lshrrev_b32_e32 v23, 1, v0
	s_ashr_i32 s15, s1, 6
	v_and_b32_e32 v35, 31, v38
	s_lshl_b32 s16, s13, 13
	s_and_b32 s4, s4, 0x1f80
	v_lshlrev_b32_e32 v22, 7, v0
	v_bitop3_b32 v0, v23, v144, 7 bitop3:0x6c
	s_ashr_i32 s1, s1, 7
	s_and_b32 s14, s2, 0xffffff00
	s_or_b32 s4, s16, s4
	v_lshl_or_b32 v141, v0, 4, v22
	v_lshl_or_b32 v0, s1, 5, v35
	s_lshl_b32 s2, s2, 1
	v_add_u32_e32 v134, s4, v0
	s_load_dwordx2 s[4:5], s[80:81], 0x108
	s_waitcnt lgkmcnt(0)
	v_mov_b64_e32 v[2:3], s[10:11]
	s_and_b32 s17, s2, 0x180
	s_and_b32 s0, s15, 1
	v_mad_i64_i32 v[2:3], s[18:19], v134, s45, v[2:3]
	s_lshl_b32 s42, s17, 1
	v_lshl_add_u64 v[2:3], v[2:3], 0, s[42:43]
	s_lshl_b32 s18, s0, 7
	s_mov_b32 s19, s43
	v_lshl_add_u64 v[2:3], v[2:3], 0, s[18:19]
	v_lshlrev_b32_e32 v132, 4, v144
	v_mov_b32_e32 v133, v1
	v_lshl_add_u64 v[2:3], v[2:3], 0, v[132:133]
	global_load_dwordx4 v[98:101], v[2:3], off offset:1024
	global_load_dwordx4 v[102:105], v[2:3], off offset:1056
	global_load_dwordx4 v[106:109], v[2:3], off offset:1088
	global_load_dwordx4 v[110:113], v[2:3], off offset:1120
	s_lshl_b32 s18, s13, 9
	s_or_b32 s2, s17, s18
	s_add_i32 s3, s14, 0x4000
	s_mul_hi_i32 s13, s2, 0x4200
	s_mulk_i32 s2, 0x4200
	v_bfe_u32 v36, v38, 3, 3
	s_add_u32 s20, s4, s2
	v_lshl_or_b32 v2, s15, 3, v36
	s_addc_u32 s21, s5, s13
	v_lshrrev_b32_e32 v0, 1, v2
	s_mul_i32 s24, s14, 0x1600
	s_add_u32 s10, s10, s42
	v_xor_b32_e32 v0, v0, v38
	s_addc_u32 s11, s11, 0
	v_lshlrev_b32_e32 v0, 4, v0
	s_add_i32 s13, s24, 0x5800000
	v_and_b32_e32 v37, 0x70, v0
	v_mul_lo_u32 v0, v2, s45
	s_mul_hi_i32 s2, s3, 0x1600
	s_add_u32 s22, s10, s13
	v_or_b32_e32 v0, v37, v0
	s_addc_u32 s23, s11, s2
	s_lshl_b32 s2, s15, 10
	v_lshl_add_u64 v[4:5], s[22:23], 0, v[0:1]
	s_add_i32 s13, s2, 0
	v_lshl_add_u64 v[6:7], v[4:5], 0, s[96:97]
	s_mov_b32 m0, s13
	v_mul_lo_u32 v2, v2, s65
	s_waitcnt vmcnt(0)
	s_barrier
	global_load_lds_dwordx4 v[6:7], off
	v_lshl_add_u64 v[4:5], v[4:5], 0, s[52:53]
	s_add_i32 m0, s13, 0x2000
	v_or_b32_e32 v2, v37, v2
	v_mov_b32_e32 v3, v1
	global_load_lds_dwordx4 v[4:5], off
	s_add_i32 m0, s13, 0x4000
	v_lshl_add_u64 v[8:9], s[20:21], 0, v[2:3]
	global_load_lds_dwordx4 v2, s[20:21]
	s_mov_b64 s[20:21], 0x108000
	s_add_i32 m0, s13, 0x6000
	s_addk_i32 s14, 0x4040
	s_add_i32 s24, s24, 0x5858000
	v_lshl_add_u64 v[2:3], v[8:9], 0, s[20:21]
	s_mul_hi_i32 s2, s14, 0x1600
	s_add_u32 s20, s10, s24
	s_addc_u32 s21, s11, s2
	global_load_lds_dwordx4 v[2:3], off
	v_lshl_add_u64 v[2:3], s[20:21], 0, v[0:1]
	v_lshl_add_u64 v[4:5], v[2:3], 0, s[96:97]
	s_add_i32 m0, s13, 0x8000
	v_lshl_add_u64 v[2:3], v[2:3], 0, s[52:53]
	global_load_lds_dwordx4 v[4:5], off
	s_add_i32 m0, s13, 0xa000
	v_lshl_add_u64 v[6:7], v[8:9], 0, s[46:47]
	global_load_lds_dwordx4 v[2:3], off
	s_add_i32 m0, s13, 0xc000
	s_mov_b64 s[20:21], 0x108080
	s_lshl_b32 s14, s0, 13
	global_load_lds_dwordx4 v[6:7], off
	v_lshl_add_u64 v[2:3], v[8:9], 0, s[20:21]
	s_add_i32 m0, s13, 0xe000
	s_add_i32 s2, s14, 0
	global_load_lds_dwordx4 v[2:3], off
	s_mov_b64 s[20:21], 0x58000
	s_add_i32 m0, s13, 0x10000
	v_lshl_add_u64 v[4:5], v[4:5], 0, s[20:21]
	v_lshl_add_u64 v[6:7], v[4:5], 0, s[46:47]
	global_load_lds_dwordx4 v[4:5], off
	s_add_i32 m0, s13, 0x12000
	s_mov_b64 s[20:21], 0x100
	global_load_lds_dwordx4 v[6:7], off
	v_lshl_add_u64 v[4:5], v[8:9], 0, s[20:21]
	s_add_i32 m0, s13, 0x14000
	s_mov_b64 s[20:21], 0x108100
	global_load_lds_dwordx4 v[4:5], off
	v_lshl_add_u64 v[6:7], v[8:9], 0, s[20:21]
	s_add_i32 m0, s13, 0x16000
	s_nop 0
	global_load_lds_dwordx4 v[6:7], off
	v_add_u32_e32 v24, s2, v141
	s_waitcnt vmcnt(8)
	s_barrier
	ds_read_b128 v[2:5], v24
	v_or_b32_e32 v39, 2, v144
	v_bitop3_b32 v6, v23, v39, 7 bitop3:0x6c
	v_lshl_or_b32 v145, v6, 4, v22
	v_add_u32_e32 v42, s2, v145
	ds_read_b128 v[18:21], v42
	s_waitcnt vmcnt(8) lgkmcnt(0)
	v_mfma_f32_32x32x16_bf16 v[2:17], v[2:5], v[98:101], 0
	v_or_b32_e32 v40, 4, v144
	v_bitop3_b32 v25, v23, v40, 7 bitop3:0x6c
	v_lshl_or_b32 v147, v25, 4, v22
	v_add_u32_e32 v46, s2, v147
	v_or_b32_e32 v41, 6, v144
	v_bitop3_b32 v23, v23, v41, 7 bitop3:0x6c
	v_lshl_or_b32 v148, v23, 4, v22
	v_mfma_f32_32x32x16_bf16 v[2:17], v[18:21], v[102:105], v[2:17]
	ds_read_b128 v[18:21], v46
	v_add_u32_e32 v47, s2, v148
	ds_read_b128 v[42:45], v42 offset:4096
	s_cmp_lt_i32 s15, 4
	s_waitcnt lgkmcnt(1)
	v_mfma_f32_32x32x16_bf16 v[2:17], v[18:21], v[106:109], v[2:17]
	ds_read_b128 v[18:21], v47
	s_waitcnt lgkmcnt(0)
	v_mfma_f32_32x32x16_bf16 v[2:17], v[18:21], v[110:113], v[2:17]
	ds_read_b128 v[18:21], v24 offset:4096
	s_waitcnt lgkmcnt(0)
	v_mfma_f32_32x32x16_bf16 v[18:33], v[18:21], v[98:101], 0
	v_mfma_f32_32x32x16_bf16 v[18:33], v[42:45], v[102:105], v[18:33]
	ds_read_b128 v[42:45], v46 offset:4096
	s_waitcnt lgkmcnt(0)
	v_mfma_f32_32x32x16_bf16 v[18:33], v[42:45], v[106:109], v[18:33]
	ds_read_b128 v[42:45], v47 offset:4096
	s_waitcnt lgkmcnt(0)
	v_mfma_f32_32x32x16_bf16 v[18:33], v[42:45], v[110:113], v[18:33]
	s_nop 1
	v_max_f32_e32 v42, v3, v3
	v_max_f32_e32 v43, v2, v2
	v_max_f32_e32 v42, v43, v42
	v_max3_f32 v42, v42, v4, v5
	v_max3_f32 v42, v42, v6, v7
	v_max3_f32 v42, v42, v8, v9
	v_max3_f32 v42, v42, v10, v11
	v_max3_f32 v42, v42, v12, v13
	v_max3_f32 v42, v42, v14, v15
	v_max3_f32 v42, v42, v16, v17
	v_max3_f32 v42, v42, v18, v19
	v_max3_f32 v42, v42, v20, v21
	v_max3_f32 v42, v42, v22, v23
	v_max3_f32 v42, v42, v24, v25
	v_max3_f32 v42, v42, v26, v27
	v_max3_f32 v42, v42, v28, v29
	v_max3_f32 v42, v42, v30, v31
	v_max3_f32 v42, v42, v32, v33
	v_mul_f32_e32 v42, 0x3e38aa3b, v42
	v_mov_b32_e32 v43, v42
	s_nop 1
	v_permlane32_swap_b32_e32 v42, v43
	s_cbranch_scc1 .LBB0_470
	s_nop 0
